# mid-epilogue grid barrier without wbl2/inv: row partial sums stored and loaded sc0 sc1 on both sides
# baseline (speedup 1.0000x reference)
.LBB0_532:
	v_and_b32_e32 v130, 64, v209
	s_lshl_b32 s6, s81, 8
	v_xor_b32_e32 v0, 16, v209
	v_add_u32_e32 v130, 64, v130
	s_add_i32 s6, s6, s47
	v_cmp_lt_i32_e32 vcc, v0, v130
	v_xor_b32_e32 v131, 32, v209
	s_lshl_b32 s0, s34, 5
	v_add_u32_e32 v194, s6, v145
	s_lshl_b32 s6, s84, 8
	v_cndmask_b32_e32 v0, v209, v0, vcc
	v_cmp_lt_i32_e32 vcc, v131, v130
	s_or_b32 s0, s6, s0
	v_ashrrev_i32_e32 v195, 31, v194
	v_cndmask_b32_e32 v130, v209, v131, vcc
	v_lshl_or_b32 v166, v144, 3, s0
	v_lshlrev_b32_e32 v172, 2, v130
	v_lshlrev_b64 v[130:131], 12, v[194:195]
	v_ashrrev_i32_e32 v167, 31, v166
	v_lshl_add_u64 v[130:131], s[16:17], 0, v[130:131]
	v_lshl_add_u64 v[138:139], v[166:167], 2, v[130:131]
	s_barrier
	v_lshlrev_b32_e32 v0, 2, v0
	v_mov_b32_e32 v251, v172
	v_cmp_eq_u32_e32 vcc, 0, v144
	v_lshlrev_b32_e32 v200, 12, v194
	v_lshl_add_u32 v200, v166, 2, v200
	s_lshl_b32 s6, s84, 2
	s_ashr_i32 s7, s6, 31
	s_lshl_b64 s[6:7], s[6:7], 2
	s_add_u32 s0, s22, s6
	s_addc_u32 s7, s23, s7
	s_lshl_b32 s6, s34, 2
	s_add_u32 s6, s0, s6
	s_addc_u32 s7, s7, 0
	v_readlane_b32 s28, v254, 39
	s_mov_b32 s98, s36
	s_mov_b32 s83, 0x800000
	v_readlane_b32 s29, v254, 40
	v_readlane_b32 s48, v254, 41
	s_mov_b64 s[34:35], s[50:51]
	v_readlane_b32 s49, v254, 42
	s_mov_b64 s[8:9], s[16:17]
	global_load_dwordx4 v[150:153], v200, s[8:9]
	global_load_dwordx4 v[146:149], v200, s[8:9] offset:16
	global_load_dwordx4 v[154:157], v200, s[8:9] offset:512
	global_load_dwordx4 v[158:161], v200, s[8:9] offset:528
	s_add_u32 s8, s16, 0x10000
	s_addc_u32 s9, s17, 0
	global_load_dwordx4 v[134:137], v200, s[8:9]
	global_load_dwordx4 v[130:133], v200, s[8:9] offset:16
	global_load_dwordx4 v[138:141], v200, s[8:9] offset:512
	global_load_dwordx4 v[142:145], v200, s[8:9] offset:528
	s_add_u32 s8, s16, 0x20000
	s_addc_u32 s9, s17, 0
	global_load_dwordx4 v[210:213], v200, s[8:9]
	global_load_dwordx4 v[214:217], v200, s[8:9] offset:16
	global_load_dwordx4 v[218:221], v200, s[8:9] offset:512
	global_load_dwordx4 v[222:225], v200, s[8:9] offset:528
	s_add_u32 s8, s16, 0x30000
	s_addc_u32 s9, s17, 0
	global_load_dwordx4 v[226:229], v200, s[8:9]
	global_load_dwordx4 v[230:233], v200, s[8:9] offset:16
	global_load_dwordx4 v[234:237], v200, s[8:9] offset:512
	global_load_dwordx4 v[238:241], v200, s[8:9] offset:528
	s_waitcnt vmcnt(12)
	v_pk_fma_f32 v[150:151], s[18:19], v[126:127], v[150:151]
	v_pk_fma_f32 v[152:153], s[24:25], v[128:129], v[152:153]
	v_pk_fma_f32 v[146:147], s[18:19], v[122:123], v[146:147]
	v_pk_fma_f32 v[148:149], s[24:25], v[124:125], v[148:149]
	v_pk_fma_f32 v[154:155], s[18:19], v[118:119], v[154:155]
	v_pk_fma_f32 v[156:157], s[24:25], v[120:121], v[156:157]
	v_pk_fma_f32 v[158:159], s[18:19], v[114:115], v[158:159]
	v_pk_fma_f32 v[160:161], s[24:25], v[116:117], v[160:161]
	v_mul_f32_e32 v202, v153, v153
	v_mul_f32_e32 v201, v151, v151
	v_fmac_f32_e32 v201, v150, v150
	v_fmac_f32_e32 v202, v152, v152
	v_add_f32_e32 v201, v201, v202
	v_mul_f32_e32 v206, v149, v149
	v_mul_f32_e32 v203, v147, v147
	v_fmac_f32_e32 v203, v146, v146
	v_fmac_f32_e32 v206, v148, v148
	v_add_f32_e32 v203, v203, v206
	v_add_f32_e32 v201, v201, v203
	v_mul_f32_e32 v206, v157, v157
	v_mul_f32_e32 v203, v155, v155
	v_fmac_f32_e32 v203, v154, v154
	v_fmac_f32_e32 v206, v156, v156
	v_add_f32_e32 v203, v203, v206
	v_mul_f32_e32 v206, v161, v161
	v_mul_f32_e32 v202, v159, v159
	v_fmac_f32_e32 v202, v158, v158
	v_fmac_f32_e32 v206, v160, v160
	v_add_f32_e32 v202, v202, v206
	v_add_f32_e32 v203, v203, v202
	v_add_f32_e32 v242, v201, v203
	s_add_u32 s8, s16, 0x80000
	s_addc_u32 s9, s17, 0
	global_load_dwordx4 v[114:117], v200, s[8:9]
	global_load_dwordx4 v[118:121], v200, s[8:9] offset:16
	global_load_dwordx4 v[122:125], v200, s[8:9] offset:512
	global_load_dwordx4 v[126:129], v200, s[8:9] offset:528
	s_waitcnt vmcnt(12)
	v_pk_fma_f32 v[134:135], s[18:19], v[110:111], v[134:135]
	v_pk_fma_f32 v[136:137], s[24:25], v[112:113], v[136:137]
	v_pk_fma_f32 v[130:131], s[18:19], v[106:107], v[130:131]
	v_pk_fma_f32 v[132:133], s[24:25], v[108:109], v[132:133]
	v_pk_fma_f32 v[138:139], s[18:19], v[102:103], v[138:139]
	v_pk_fma_f32 v[140:141], s[24:25], v[104:105], v[140:141]
	v_pk_fma_f32 v[142:143], s[18:19], v[98:99], v[142:143]
	v_pk_fma_f32 v[144:145], s[24:25], v[100:101], v[144:145]
	v_mul_f32_e32 v202, v137, v137
	v_mul_f32_e32 v201, v135, v135
	v_fmac_f32_e32 v201, v134, v134
	v_fmac_f32_e32 v202, v136, v136
	v_add_f32_e32 v201, v201, v202
	v_mul_f32_e32 v206, v133, v133
	v_mul_f32_e32 v203, v131, v131
	v_fmac_f32_e32 v203, v130, v130
	v_fmac_f32_e32 v206, v132, v132
	v_add_f32_e32 v203, v203, v206
	v_add_f32_e32 v201, v201, v203
	v_mul_f32_e32 v206, v141, v141
	v_mul_f32_e32 v203, v139, v139
	v_fmac_f32_e32 v203, v138, v138
	v_fmac_f32_e32 v206, v140, v140
	v_add_f32_e32 v203, v203, v206
	v_mul_f32_e32 v206, v145, v145
	v_mul_f32_e32 v202, v143, v143
	v_fmac_f32_e32 v202, v142, v142
	v_fmac_f32_e32 v206, v144, v144
	v_add_f32_e32 v202, v202, v206
	v_add_f32_e32 v203, v203, v202
	v_add_f32_e32 v243, v201, v203
	s_add_u32 s8, s16, 0x90000
	s_addc_u32 s9, s17, 0
	global_load_dwordx4 v[98:101], v200, s[8:9]
	global_load_dwordx4 v[102:105], v200, s[8:9] offset:16
	global_load_dwordx4 v[106:109], v200, s[8:9] offset:512
	global_load_dwordx4 v[110:113], v200, s[8:9] offset:528
	s_waitcnt vmcnt(12)
	v_pk_fma_f32 v[86:87], s[18:19], v[86:87], v[210:211]
	v_pk_fma_f32 v[88:89], s[24:25], v[88:89], v[212:213]
	v_pk_fma_f32 v[82:83], s[18:19], v[82:83], v[214:215]
	v_pk_fma_f32 v[84:85], s[24:25], v[84:85], v[216:217]
	v_pk_fma_f32 v[90:91], s[18:19], v[90:91], v[218:219]
	v_pk_fma_f32 v[92:93], s[24:25], v[92:93], v[220:221]
	v_pk_fma_f32 v[94:95], s[18:19], v[94:95], v[222:223]
	v_pk_fma_f32 v[96:97], s[24:25], v[96:97], v[224:225]
	v_mul_f32_e32 v202, v89, v89
	v_mul_f32_e32 v201, v87, v87
	v_fmac_f32_e32 v201, v86, v86
	v_fmac_f32_e32 v202, v88, v88
	v_add_f32_e32 v201, v201, v202
	v_mul_f32_e32 v206, v85, v85
	v_mul_f32_e32 v203, v83, v83
	v_fmac_f32_e32 v203, v82, v82
	v_fmac_f32_e32 v206, v84, v84
	v_add_f32_e32 v203, v203, v206
	v_add_f32_e32 v201, v201, v203
	v_mul_f32_e32 v206, v93, v93
	v_mul_f32_e32 v203, v91, v91
	v_fmac_f32_e32 v203, v90, v90
	v_fmac_f32_e32 v206, v92, v92
	v_add_f32_e32 v203, v203, v206
	v_mul_f32_e32 v206, v97, v97
	v_mul_f32_e32 v202, v95, v95
	v_fmac_f32_e32 v202, v94, v94
	v_fmac_f32_e32 v206, v96, v96
	v_add_f32_e32 v202, v202, v206
	v_add_f32_e32 v203, v203, v202
	v_add_f32_e32 v244, v201, v203
	s_add_u32 s8, s16, 0xa0000
	s_addc_u32 s9, s17, 0
	global_load_dwordx4 v[210:213], v200, s[8:9]
	global_load_dwordx4 v[214:217], v200, s[8:9] offset:16
	global_load_dwordx4 v[218:221], v200, s[8:9] offset:512
	global_load_dwordx4 v[222:225], v200, s[8:9] offset:528
	s_waitcnt vmcnt(12)
	v_pk_fma_f32 v[70:71], s[18:19], v[70:71], v[226:227]
	v_pk_fma_f32 v[72:73], s[24:25], v[72:73], v[228:229]
	v_pk_fma_f32 v[66:67], s[18:19], v[66:67], v[230:231]
	v_pk_fma_f32 v[68:69], s[24:25], v[68:69], v[232:233]
	v_pk_fma_f32 v[74:75], s[18:19], v[74:75], v[234:235]
	v_pk_fma_f32 v[76:77], s[24:25], v[76:77], v[236:237]
	v_pk_fma_f32 v[78:79], s[18:19], v[78:79], v[238:239]
	v_pk_fma_f32 v[80:81], s[24:25], v[80:81], v[240:241]
	v_mul_f32_e32 v202, v73, v73
	v_mul_f32_e32 v201, v71, v71
	v_fmac_f32_e32 v201, v70, v70
	v_fmac_f32_e32 v202, v72, v72
	v_add_f32_e32 v201, v201, v202
	v_mul_f32_e32 v206, v69, v69
	v_mul_f32_e32 v203, v67, v67
	v_fmac_f32_e32 v203, v66, v66
	v_fmac_f32_e32 v206, v68, v68
	v_add_f32_e32 v203, v203, v206
	v_add_f32_e32 v201, v201, v203
	v_mul_f32_e32 v206, v77, v77
	v_mul_f32_e32 v203, v75, v75
	v_fmac_f32_e32 v203, v74, v74
	v_fmac_f32_e32 v206, v76, v76
	v_add_f32_e32 v203, v203, v206
	v_mul_f32_e32 v206, v81, v81
	v_mul_f32_e32 v202, v79, v79
	v_fmac_f32_e32 v202, v78, v78
	v_fmac_f32_e32 v206, v80, v80
	v_add_f32_e32 v202, v202, v206
	v_add_f32_e32 v203, v203, v202
	v_add_f32_e32 v245, v201, v203
	s_add_u32 s8, s16, 0xb0000
	s_addc_u32 s9, s17, 0
	global_load_dwordx4 v[226:229], v200, s[8:9]
	global_load_dwordx4 v[230:233], v200, s[8:9] offset:16
	global_load_dwordx4 v[234:237], v200, s[8:9] offset:512
	global_load_dwordx4 v[238:241], v200, s[8:9] offset:528
	s_waitcnt vmcnt(12)
	v_pk_fma_f32 v[54:55], s[18:19], v[54:55], v[114:115]
	v_pk_fma_f32 v[56:57], s[24:25], v[56:57], v[116:117]
	v_pk_fma_f32 v[50:51], s[18:19], v[50:51], v[118:119]
	v_pk_fma_f32 v[52:53], s[24:25], v[52:53], v[120:121]
	v_pk_fma_f32 v[58:59], s[18:19], v[58:59], v[122:123]
	v_pk_fma_f32 v[60:61], s[24:25], v[60:61], v[124:125]
	v_pk_fma_f32 v[62:63], s[18:19], v[62:63], v[126:127]
	v_pk_fma_f32 v[64:65], s[24:25], v[64:65], v[128:129]
	v_mul_f32_e32 v202, v57, v57
	v_mul_f32_e32 v201, v55, v55
	v_fmac_f32_e32 v201, v54, v54
	v_fmac_f32_e32 v202, v56, v56
	v_add_f32_e32 v201, v201, v202
	v_mul_f32_e32 v206, v53, v53
	v_mul_f32_e32 v203, v51, v51
	v_fmac_f32_e32 v203, v50, v50
	v_fmac_f32_e32 v206, v52, v52
	v_add_f32_e32 v203, v203, v206
	v_add_f32_e32 v201, v201, v203
	v_mul_f32_e32 v206, v61, v61
	v_mul_f32_e32 v203, v59, v59
	v_fmac_f32_e32 v203, v58, v58
	v_fmac_f32_e32 v206, v60, v60
	v_add_f32_e32 v203, v203, v206
	v_mul_f32_e32 v206, v65, v65
	v_mul_f32_e32 v202, v63, v63
	v_fmac_f32_e32 v202, v62, v62
	v_fmac_f32_e32 v206, v64, v64
	v_add_f32_e32 v202, v202, v206
	v_add_f32_e32 v203, v203, v202
	v_add_f32_e32 v246, v201, v203
	s_waitcnt vmcnt(8)
	v_pk_fma_f32 v[38:39], s[18:19], v[38:39], v[98:99]
	v_pk_fma_f32 v[40:41], s[24:25], v[40:41], v[100:101]
	v_pk_fma_f32 v[34:35], s[18:19], v[34:35], v[102:103]
	v_pk_fma_f32 v[36:37], s[24:25], v[36:37], v[104:105]
	v_pk_fma_f32 v[42:43], s[18:19], v[42:43], v[106:107]
	v_pk_fma_f32 v[44:45], s[24:25], v[44:45], v[108:109]
	v_pk_fma_f32 v[46:47], s[18:19], v[46:47], v[110:111]
	v_pk_fma_f32 v[48:49], s[24:25], v[48:49], v[112:113]
	v_mul_f32_e32 v202, v41, v41
	v_mul_f32_e32 v201, v39, v39
	v_fmac_f32_e32 v201, v38, v38
	v_fmac_f32_e32 v202, v40, v40
	v_add_f32_e32 v201, v201, v202
	v_mul_f32_e32 v206, v37, v37
	v_mul_f32_e32 v203, v35, v35
	v_fmac_f32_e32 v203, v34, v34
	v_fmac_f32_e32 v206, v36, v36
	v_add_f32_e32 v203, v203, v206
	v_add_f32_e32 v201, v201, v203
	v_mul_f32_e32 v206, v45, v45
	v_mul_f32_e32 v203, v43, v43
	v_fmac_f32_e32 v203, v42, v42
	v_fmac_f32_e32 v206, v44, v44
	v_add_f32_e32 v203, v203, v206
	v_mul_f32_e32 v206, v49, v49
	v_mul_f32_e32 v202, v47, v47
	v_fmac_f32_e32 v202, v46, v46
	v_fmac_f32_e32 v206, v48, v48
	v_add_f32_e32 v202, v202, v206
	v_add_f32_e32 v203, v203, v202
	v_add_f32_e32 v247, v201, v203
	s_waitcnt vmcnt(4)
	v_pk_fma_f32 v[22:23], s[18:19], v[22:23], v[210:211]
	v_pk_fma_f32 v[24:25], s[24:25], v[24:25], v[212:213]
	v_pk_fma_f32 v[18:19], s[18:19], v[18:19], v[214:215]
	v_pk_fma_f32 v[20:21], s[24:25], v[20:21], v[216:217]
	v_pk_fma_f32 v[26:27], s[18:19], v[26:27], v[218:219]
	v_pk_fma_f32 v[28:29], s[24:25], v[28:29], v[220:221]
	v_pk_fma_f32 v[30:31], s[18:19], v[30:31], v[222:223]
	v_pk_fma_f32 v[32:33], s[24:25], v[32:33], v[224:225]
	v_mul_f32_e32 v202, v25, v25
	v_mul_f32_e32 v201, v23, v23
	v_fmac_f32_e32 v201, v22, v22
	v_fmac_f32_e32 v202, v24, v24
	v_add_f32_e32 v201, v201, v202
	v_mul_f32_e32 v206, v21, v21
	v_mul_f32_e32 v203, v19, v19
	v_fmac_f32_e32 v203, v18, v18
	v_fmac_f32_e32 v206, v20, v20
	v_add_f32_e32 v203, v203, v206
	v_add_f32_e32 v201, v201, v203
	v_mul_f32_e32 v206, v29, v29
	v_mul_f32_e32 v203, v27, v27
	v_fmac_f32_e32 v203, v26, v26
	v_fmac_f32_e32 v206, v28, v28
	v_add_f32_e32 v203, v203, v206
	v_mul_f32_e32 v206, v33, v33
	v_mul_f32_e32 v202, v31, v31
	v_fmac_f32_e32 v202, v30, v30
	v_fmac_f32_e32 v206, v32, v32
	v_add_f32_e32 v202, v202, v206
	v_add_f32_e32 v203, v203, v202
	v_add_f32_e32 v248, v201, v203
	s_waitcnt vmcnt(0)
	v_pk_fma_f32 v[6:7], s[18:19], v[6:7], v[226:227]
	v_pk_fma_f32 v[8:9], s[24:25], v[8:9], v[228:229]
	v_pk_fma_f32 v[2:3], s[18:19], v[2:3], v[230:231]
	v_pk_fma_f32 v[4:5], s[24:25], v[4:5], v[232:233]
	v_pk_fma_f32 v[10:11], s[18:19], v[10:11], v[234:235]
	v_pk_fma_f32 v[12:13], s[24:25], v[12:13], v[236:237]
	v_pk_fma_f32 v[14:15], s[18:19], v[14:15], v[238:239]
	v_pk_fma_f32 v[16:17], s[24:25], v[16:17], v[240:241]
	v_mul_f32_e32 v202, v9, v9
	v_mul_f32_e32 v201, v7, v7
	v_fmac_f32_e32 v201, v6, v6
	v_fmac_f32_e32 v202, v8, v8
	v_add_f32_e32 v201, v201, v202
	v_mul_f32_e32 v206, v5, v5
	v_mul_f32_e32 v203, v3, v3
	v_fmac_f32_e32 v203, v2, v2
	v_fmac_f32_e32 v206, v4, v4
	v_add_f32_e32 v203, v203, v206
	v_add_f32_e32 v201, v201, v203
	v_mul_f32_e32 v206, v13, v13
	v_mul_f32_e32 v203, v11, v11
	v_fmac_f32_e32 v203, v10, v10
	v_fmac_f32_e32 v206, v12, v12
	v_add_f32_e32 v203, v203, v206
	v_mul_f32_e32 v206, v17, v17
	v_mul_f32_e32 v202, v15, v15
	v_fmac_f32_e32 v202, v14, v14
	v_fmac_f32_e32 v206, v16, v16
	v_add_f32_e32 v202, v202, v206
	v_add_f32_e32 v203, v203, v202
	v_add_f32_e32 v249, v201, v203
	ds_bpermute_b32 v168, v0, v242
	ds_bpermute_b32 v169, v0, v243
	ds_bpermute_b32 v170, v0, v244
	ds_bpermute_b32 v171, v0, v245
	ds_bpermute_b32 v172, v0, v246
	ds_bpermute_b32 v173, v0, v247
	ds_bpermute_b32 v174, v0, v248
	ds_bpermute_b32 v175, v0, v249
	s_waitcnt lgkmcnt(0)
	v_add_f32_e32 v242, v242, v168
	v_add_f32_e32 v243, v243, v169
	v_add_f32_e32 v244, v244, v170
	v_add_f32_e32 v245, v245, v171
	v_add_f32_e32 v246, v246, v172
	v_add_f32_e32 v247, v247, v173
	v_add_f32_e32 v248, v248, v174
	v_add_f32_e32 v249, v249, v175
	ds_bpermute_b32 v168, v251, v242
	ds_bpermute_b32 v169, v251, v243
	ds_bpermute_b32 v170, v251, v244
	ds_bpermute_b32 v171, v251, v245
	ds_bpermute_b32 v172, v251, v246
	ds_bpermute_b32 v173, v251, v247
	ds_bpermute_b32 v174, v251, v248
	ds_bpermute_b32 v175, v251, v249
	v_lshlrev_b32_e32 v201, 6, v194
	v_add_u32_e32 v202, 0x2000, v201
	s_waitcnt lgkmcnt(0)
	v_add_f32_e32 v242, v242, v168
	v_add_f32_e32 v243, v243, v169
	v_add_f32_e32 v244, v244, v170
	v_add_f32_e32 v245, v245, v171
	v_add_f32_e32 v246, v246, v172
	v_add_f32_e32 v247, v247, v173
	v_add_f32_e32 v248, v248, v174
	v_add_f32_e32 v249, v249, v175
	s_and_saveexec_b64 s[8:9], vcc
	global_store_dword v201, v242, s[6:7] sc0 sc1
	global_store_dword v201, v243, s[6:7] offset:1024 sc0 sc1
	global_store_dword v201, v244, s[6:7] offset:2048 sc0 sc1
	global_store_dword v201, v245, s[6:7] offset:3072 sc0 sc1
	global_store_dword v202, v246, s[6:7] sc0 sc1
	global_store_dword v202, v247, s[6:7] offset:1024 sc0 sc1
	global_store_dword v202, v248, s[6:7] offset:2048 sc0 sc1
	global_store_dword v202, v249, s[6:7] offset:3072 sc0 sc1
	s_or_b64 exec, exec, s[8:9]
	s_getreg_b32 s0, hwreg(HW_REG_XCC_ID, 0, 4)
	s_waitcnt vmcnt(0)
	s_waitcnt lgkmcnt(0)
	s_barrier
	s_mov_b64 s[6:7], exec
	v_readlane_b32 s8, v252, 4
	v_readlane_b32 s9, v252, 5
	s_and_b64 s[8:9], s[6:7], s[8:9]
	s_xor_b64 s[6:7], s[8:9], s[6:7]
	s_mov_b64 exec, s[8:9]
	s_cbranch_execz .LBB0_601
	v_readlane_b32 s8, v253, 9
	s_waitcnt vmcnt(0) expcnt(0) lgkmcnt(0)
	s_and_b32 s0, s0, 15
	v_mov_b32_e32 v0, s8
	ds_read_b32 v99, v0
	v_readlane_b32 s8, v253, 10
	s_waitcnt lgkmcnt(0)
	v_cmp_ne_u32_e32 vcc, 0, v99
	v_mov_b32_e32 v0, s8
	ds_read_b32 v98, v0
	s_cbranch_vccnz .LBB0_564
	s_mov_b32 s14, 1
	s_branch .LBB0_552

.LBB0_580:
	s_andn2_saveexec_b64 s[10:11], s[10:11]
	s_cbranch_execz .LBB0_600
	s_mov_b64 s[74:75], exec
	s_waitcnt lgkmcnt(0)
	s_waitcnt vmcnt(0)
	v_mbcnt_lo_u32_b32 v0, s74, 0
	v_mbcnt_hi_u32_b32 v0, s75, v0
	v_cmp_eq_u32_e32 vcc, 0, v0
	s_and_saveexec_b64 s[88:89], vcc
	s_cbranch_execz .LBB0_583
	s_bcnt1_i32_b64 s0, s[74:75]
	v_readlane_b32 s14, v254, 31
	v_mov_b32_e32 v99, s0
	v_readlane_b32 s15, v254, 32
	s_nop 4
	global_atomic_add v99, v1, v99, s[14:15] sc0

.LBB0_601:
	s_or_b64 exec, exec, s[6:7]
	s_mov_b64 s[84:85], s[62:63]
	s_mov_b64 s[80:81], s[60:61]
	s_mov_b64 s[74:75], s[58:59]
	s_mov_b64 s[28:29], s[56:57]
	s_mov_b64 s[14:15], s[54:55]
	s_mov_b64 s[10:11], s[52:53]
	v_readlane_b32 s6, v254, 27
	v_readlane_b32 s7, v254, 28
	v_readlane_b32 s8, v253, 38
	v_readlane_b32 s9, v253, 39
	v_readlane_b32 s48, v253, 56
	v_readlane_b32 s49, v253, 57
	v_readlane_b32 s50, v254, 8
	v_readlane_b32 s51, v254, 9
	v_readlane_b32 s52, v254, 6
	v_readlane_b32 s53, v254, 7
	s_waitcnt lgkmcnt(0)
	s_barrier
	v_bfe_u32 v201, v204, 4, 2
	v_lshlrev_b32_e32 v202, 2, v166
	v_lshlrev_b32_e32 v203, 6, v194
	v_lshl_add_u32 v203, v201, 4, v203
	v_add_u32_e32 v206, 0x2000, v203
	v_xor_b32_e32 v207, 16, v209
	v_xor_b32_e32 v250, 32, v209
	v_lshlrev_b32_e32 v207, 2, v207
	v_lshlrev_b32_e32 v250, 2, v250
	global_load_dwordx4 v[210:213], v203, s[22:23] sc0 sc1
	global_load_dwordx4 v[214:217], v203, s[22:23] offset:1024 sc0 sc1
	global_load_dwordx4 v[218:221], v203, s[22:23] offset:2048 sc0 sc1
	global_load_dwordx4 v[222:225], v203, s[22:23] offset:3072 sc0 sc1
	global_load_dwordx4 v[226:229], v206, s[22:23] sc0 sc1
	global_load_dwordx4 v[230:233], v206, s[22:23] offset:1024 sc0 sc1
	global_load_dwordx4 v[234:237], v206, s[22:23] offset:2048 sc0 sc1
	global_load_dwordx4 v[238:241], v206, s[22:23] offset:3072 sc0 sc1
	global_load_dwordx4 v[122:125], v202, s[6:7]
	global_load_dwordx4 v[118:121], v202, s[6:7] offset:16
	global_load_dwordx4 v[110:113], v202, s[6:7] offset:512
	global_load_dwordx4 v[106:109], v202, s[6:7] offset:528
	s_and_b64 vcc, exec, s[8:9]
	s_cbranch_vccz .Lrn_g2_done
	global_load_dwordx4 v[114:117], v202, s[48:49]
	global_load_dwordx4 v[126:129], v202, s[48:49] offset:16
	global_load_dwordx4 v[98:101], v202, s[48:49] offset:512
	global_load_dwordx4 v[102:105], v202, s[48:49] offset:528
